# ret_sample: q/k/v + 8 state loads + gate load batched before first barrier; ret_local second load pair hoisted
# speedup vs baseline: 1.0407x; 1.0093x over previous
.LBB0_544:
	s_andn2_b64 vcc, exec, s[0:1]
	s_cbranch_vccnz .LBB0_548
	v_readlane_b32 s0, v244, 58
	s_and_b32 s4, s0, 7
	v_cvt_f32_ubyte0_e32 v0, s4
	s_add_i32 s5, s0, 0xfffff500
	v_sub_f32_e32 v0, 0xc0a00000, v0
	s_mov_b32 s0, 0xc2fc0000
	v_cmp_gt_f32_e32 vcc, s0, v0
	s_and_b32 s6, s5, 0x3f8
	s_and_b64 s[0:1], vcc, exec
	v_cndmask_b32_e32 v1, 0, v201, vcc
	v_add_f32_e32 v0, v0, v1
	v_exp_f32_e32 v0, v0
	s_cselect_b32 s0, 0xffffffc0, 0
	v_add_u32_e32 v42, s6, v45
	s_lshl_b32 s4, s4, 6
	v_ldexp_f32 v0, v0, s0
	v_sub_f32_e32 v0, 1.0, v0
	v_log_f32_e32 v16, v0
	v_lshlrev_b64 v[0:1], 9, v[42:43]
	v_or_b32_e32 v0, s4, v0
	v_or_b32_e32 v0, v0, v40
	v_readlane_b32 s0, v244, 32
	v_lshlrev_b64 v[2:3], 1, v[0:1]
	v_readlane_b32 s1, v244, 33
	s_nop 1
	v_lshl_add_u64 v[4:5], s[0:1], 0, v[2:3]
	global_load_ushort v6, v[4:5], off
	v_readlane_b32 s0, v244, 38
	v_readlane_b32 s1, v244, 39
	s_nop 1
	v_lshl_add_u64 v[4:5], s[0:1], 0, v[2:3]
	v_readlane_b32 s0, v244, 40
	v_readlane_b32 s1, v244, 41
	global_load_ushort v4, v[4:5], off
	s_nop 0
	v_lshl_add_u64 v[2:3], s[0:1], 0, v[2:3]
	global_load_ushort v2, v[2:3], off
	v_lshl_add_u32 v8, s5, 12, v135
	v_mov_b32_e32 v9, v43
	v_lshlrev_b64 v[8:9], 2, v[8:9]
	v_lshl_add_u64 v[10:11], v[56:57], 0, v[8:9]
	global_load_dword v23, v[10:11], off nt
	global_load_dword v24, v[10:11], off offset:256 nt
	global_load_dword v21, v[10:11], off offset:512 nt
	global_load_dword v22, v[10:11], off offset:768 nt
	global_load_dword v19, v[10:11], off offset:1024 nt
	global_load_dword v20, v[10:11], off offset:1280 nt
	global_load_dword v18, v[10:11], off offset:1536 nt
	global_load_dword v17, v[10:11], off offset:1792 nt
	s_barrier
	s_waitcnt vmcnt(10)
	v_lshlrev_b32_e32 v6, 16, v6
	s_waitcnt vmcnt(9)
	v_lshlrev_b32_e32 v4, 16, v4
	ds_write2st64_b32 v55, v6, v4 offset1:8
	s_waitcnt vmcnt(8)
	v_lshlrev_b32_e32 v2, 16, v2
	ds_write_b32 v55, v2 offset:4096
	s_waitcnt lgkmcnt(0)
	s_barrier
	s_mov_b64 s[0:1], exec
	v_readlane_b32 s6, v245, 4
	v_readlane_b32 s7, v245, 5
	s_and_b64 s[6:7], s[0:1], s[6:7]
	s_mov_b64 exec, s[6:7]
	s_cbranch_execz .LBB0_547
	ds_read2_b32 v[2:3], v132 offset1:1
	ds_read2_b32 v[4:5], v203 offset1:1
	v_readlane_b32 s6, v245, 6
	v_readlane_b32 s7, v245, 7
	s_waitcnt lgkmcnt(0)
	v_fma_f32 v2, v2, v4, 0
	v_fmac_f32_e32 v2, v3, v5
	ds_read2_b32 v[4:5], v132 offset0:2 offset1:3
	ds_read2_b32 v[6:7], v204 offset1:1
	v_add_u32_e32 v3, 0x840, v133
	s_waitcnt lgkmcnt(0)
	v_fmac_f32_e32 v2, v4, v6
	v_fmac_f32_e32 v2, v5, v7
	ds_read2_b32 v[4:5], v132 offset0:4 offset1:5
	ds_read2_b32 v[6:7], v205 offset1:1
	s_waitcnt lgkmcnt(0)
	v_fmac_f32_e32 v2, v4, v6
	v_fmac_f32_e32 v2, v5, v7
	ds_read2_b32 v[4:5], v132 offset0:6 offset1:7
	ds_read2_b32 v[6:7], v206 offset1:1
	s_waitcnt lgkmcnt(0)
	v_fmac_f32_e32 v2, v4, v6
	v_fmac_f32_e32 v2, v5, v7
	ds_read2_b32 v[4:5], v132 offset0:8 offset1:9
	ds_read2_b32 v[6:7], v207 offset1:1
	s_waitcnt lgkmcnt(0)
	v_fmac_f32_e32 v2, v4, v6
	v_fmac_f32_e32 v2, v5, v7
	ds_read2_b32 v[4:5], v132 offset0:10 offset1:11
	ds_read2_b32 v[6:7], v208 offset1:1
	s_waitcnt lgkmcnt(0)
	v_fmac_f32_e32 v2, v4, v6
	v_fmac_f32_e32 v2, v5, v7
	ds_read2_b32 v[4:5], v132 offset0:12 offset1:13
	ds_read2_b32 v[6:7], v209 offset1:1
	s_waitcnt lgkmcnt(0)
	v_fmac_f32_e32 v2, v4, v6
	v_fmac_f32_e32 v2, v5, v7
	ds_read2_b32 v[4:5], v132 offset0:14 offset1:15
	ds_read2_b32 v[6:7], v210 offset1:1
	s_waitcnt lgkmcnt(0)
	v_fmac_f32_e32 v2, v4, v6
	v_fmac_f32_e32 v2, v5, v7
	ds_read2_b32 v[4:5], v132 offset0:16 offset1:17
	ds_read2_b32 v[6:7], v3 offset1:1
	v_add_u32_e32 v3, 0x848, v133
	s_waitcnt lgkmcnt(0)
	v_fmac_f32_e32 v2, v4, v6
	v_fmac_f32_e32 v2, v5, v7
	ds_read2_b32 v[4:5], v132 offset0:18 offset1:19
	ds_read2_b32 v[6:7], v3 offset1:1
	v_add_u32_e32 v3, 0x850, v133
	s_waitcnt lgkmcnt(0)
	v_fmac_f32_e32 v2, v4, v6
	v_fmac_f32_e32 v2, v5, v7
	ds_read2_b32 v[4:5], v132 offset0:20 offset1:21
	ds_read2_b32 v[6:7], v3 offset1:1
	v_add_u32_e32 v3, 0x858, v133
	s_waitcnt lgkmcnt(0)
	v_fmac_f32_e32 v2, v4, v6
	v_fmac_f32_e32 v2, v5, v7
	ds_read2_b32 v[4:5], v132 offset0:22 offset1:23
	ds_read2_b32 v[6:7], v3 offset1:1
	v_add_u32_e32 v3, 0x860, v133
	s_waitcnt lgkmcnt(0)
	v_fmac_f32_e32 v2, v4, v6
	v_fmac_f32_e32 v2, v5, v7
	ds_read2_b32 v[4:5], v132 offset0:24 offset1:25
	ds_read2_b32 v[6:7], v3 offset1:1
	v_add_u32_e32 v3, 0x868, v133
	s_waitcnt lgkmcnt(0)
	v_fmac_f32_e32 v2, v4, v6
	v_fmac_f32_e32 v2, v5, v7
	ds_read2_b32 v[4:5], v132 offset0:26 offset1:27
	ds_read2_b32 v[6:7], v3 offset1:1
	v_add_u32_e32 v3, 0x870, v133
	s_waitcnt lgkmcnt(0)
	v_fmac_f32_e32 v2, v4, v6
	v_fmac_f32_e32 v2, v5, v7
	ds_read2_b32 v[4:5], v132 offset0:28 offset1:29
	ds_read2_b32 v[6:7], v3 offset1:1
	v_add_u32_e32 v3, 0x878, v133
	s_waitcnt lgkmcnt(0)
	v_fmac_f32_e32 v2, v4, v6
	v_fmac_f32_e32 v2, v5, v7
	ds_read2_b32 v[4:5], v132 offset0:30 offset1:31
	ds_read2_b32 v[6:7], v3 offset1:1
	v_add_u32_e32 v3, 0x880, v133
	s_waitcnt lgkmcnt(0)
	v_fmac_f32_e32 v2, v4, v6
	v_fmac_f32_e32 v2, v5, v7
	ds_read2_b32 v[4:5], v132 offset0:32 offset1:33
	ds_read2_b32 v[6:7], v3 offset1:1
	v_add_u32_e32 v3, 0x888, v133
	s_waitcnt lgkmcnt(0)
	v_fmac_f32_e32 v2, v4, v6
	v_fmac_f32_e32 v2, v5, v7
	ds_read2_b32 v[4:5], v132 offset0:34 offset1:35
	ds_read2_b32 v[6:7], v3 offset1:1
	v_add_u32_e32 v3, 0x890, v133
	s_waitcnt lgkmcnt(0)
	v_fmac_f32_e32 v2, v4, v6
	v_fmac_f32_e32 v2, v5, v7
	ds_read2_b32 v[4:5], v132 offset0:36 offset1:37
	ds_read2_b32 v[6:7], v3 offset1:1
	v_add_u32_e32 v3, 0x898, v133
	s_waitcnt lgkmcnt(0)
	v_fmac_f32_e32 v2, v4, v6
	v_fmac_f32_e32 v2, v5, v7
	ds_read2_b32 v[4:5], v132 offset0:38 offset1:39
	ds_read2_b32 v[6:7], v3 offset1:1
	v_add_u32_e32 v3, 0x8a0, v133
	s_waitcnt lgkmcnt(0)
	v_fmac_f32_e32 v2, v4, v6
	v_fmac_f32_e32 v2, v5, v7
	ds_read2_b32 v[4:5], v132 offset0:40 offset1:41
	ds_read2_b32 v[6:7], v3 offset1:1
	v_add_u32_e32 v3, 0x8a8, v133
	s_waitcnt lgkmcnt(0)
	v_fmac_f32_e32 v2, v4, v6
	v_fmac_f32_e32 v2, v5, v7
	ds_read2_b32 v[4:5], v132 offset0:42 offset1:43
	ds_read2_b32 v[6:7], v3 offset1:1
	v_add_u32_e32 v3, 0x8b0, v133
	s_waitcnt lgkmcnt(0)
	v_fmac_f32_e32 v2, v4, v6
	v_fmac_f32_e32 v2, v5, v7
	ds_read2_b32 v[4:5], v132 offset0:44 offset1:45
	ds_read2_b32 v[6:7], v3 offset1:1
	v_add_u32_e32 v3, 0x8b8, v133
	s_waitcnt lgkmcnt(0)
	v_fmac_f32_e32 v2, v4, v6
	v_fmac_f32_e32 v2, v5, v7
	ds_read2_b32 v[4:5], v132 offset0:46 offset1:47
	ds_read2_b32 v[6:7], v3 offset1:1
	v_add_u32_e32 v3, 0x8c0, v133
	s_waitcnt lgkmcnt(0)
	v_fmac_f32_e32 v2, v4, v6
	v_fmac_f32_e32 v2, v5, v7
	ds_read2_b32 v[4:5], v132 offset0:48 offset1:49
	ds_read2_b32 v[6:7], v3 offset1:1
	v_add_u32_e32 v3, 0x8c8, v133
	s_waitcnt lgkmcnt(0)
	v_fmac_f32_e32 v2, v4, v6
	v_fmac_f32_e32 v2, v5, v7
	ds_read2_b32 v[4:5], v132 offset0:50 offset1:51
	ds_read2_b32 v[6:7], v3 offset1:1
	v_add_u32_e32 v3, 0x8d0, v133
	s_waitcnt lgkmcnt(0)
	v_fmac_f32_e32 v2, v4, v6
	v_fmac_f32_e32 v2, v5, v7
	ds_read2_b32 v[4:5], v132 offset0:52 offset1:53
	ds_read2_b32 v[6:7], v3 offset1:1
	v_add_u32_e32 v3, 0x8d8, v133
	s_waitcnt lgkmcnt(0)
	v_fmac_f32_e32 v2, v4, v6
	v_fmac_f32_e32 v2, v5, v7
	ds_read2_b32 v[4:5], v132 offset0:54 offset1:55
	ds_read2_b32 v[6:7], v3 offset1:1
	s_waitcnt lgkmcnt(0)
	v_pk_mul_f32 v[4:5], v[4:5], v[6:7]
	s_nop 0
	v_add_f32_e32 v2, v2, v4
	v_add_u32_e32 v4, 0x8e0, v133
	v_add_f32_e32 v6, v2, v5
	ds_read2_b32 v[2:3], v132 offset0:56 offset1:57
	ds_read2_b32 v[4:5], v4 offset1:1
	s_waitcnt lgkmcnt(0)
	v_pk_mul_f32 v[2:3], v[2:3], v[4:5]
	s_nop 0
	v_add_f32_e32 v2, v6, v2
	v_add_u32_e32 v4, 0x8e8, v133
	v_add_f32_e32 v6, v2, v3
	ds_read2_b32 v[2:3], v132 offset0:58 offset1:59
	ds_read2_b32 v[4:5], v4 offset1:1
	s_waitcnt lgkmcnt(0)
	v_pk_mul_f32 v[2:3], v[2:3], v[4:5]
	s_nop 0
	v_add_f32_e32 v2, v6, v2
	v_add_u32_e32 v4, 0x8f0, v133
	v_add_f32_e32 v6, v2, v3
	ds_read2_b32 v[2:3], v132 offset0:60 offset1:61
	ds_read2_b32 v[4:5], v4 offset1:1
	s_waitcnt lgkmcnt(0)
	v_pk_mul_f32 v[2:3], v[2:3], v[4:5]
	s_nop 0
	v_add_f32_e32 v2, v6, v2
	v_add_u32_e32 v4, 0x8f8, v133
	v_add_f32_e32 v6, v2, v3
	ds_read2_b32 v[2:3], v132 offset0:62 offset1:63
	ds_read2_b32 v[4:5], v4 offset1:1
	s_waitcnt lgkmcnt(0)
	v_pk_mul_f32 v[2:3], v[2:3], v[4:5]
	s_nop 0
	v_add_f32_e32 v2, v6, v2
	v_add_f32_e32 v2, v2, v3
	v_mul_f32_e32 v3, v16, v134
	v_exp_f32_e32 v3, v3
	s_nop 0
	v_mul_f32_e32 v2, v3, v2
	v_cndmask_b32_e64 v2, v2, 0, s[6:7]
	ds_write_b32 v55, v2 offset:6144
.LBB0_547:
	s_or_b64 exec, exec, s[0:1]
	v_lshl_add_u32 v2, s5, 12, v135
	v_mov_b32_e32 v3, v43
	v_lshlrev_b64 v[2:3], 2, v[2:3]
	v_mul_f32_e32 v4, 0x41000000, v16
	v_exp_f32_e32 v25, v4
	v_mul_f32_e32 v4, 0x40e00000, v16
	v_exp_f32_e32 v26, v4
	v_add_u32_e32 v4, 0x800, v136
	ds_read2_b32 v[12:13], v4 offset1:1
	ds_read2st64_b32 v[4:5], v137 offset0:16 offset1:17
	v_exp_f32_e32 v32, v16
	v_lshl_add_u64 v[2:3], v[66:67], 0, v[2:3]
	v_readlane_b32 s0, v244, 34
	s_waitcnt lgkmcnt(1)
	v_mul_f32_e32 v6, v26, v12
	s_waitcnt lgkmcnt(0)
	v_mul_f32_e32 v12, v6, v4
	v_mul_f32_e32 v6, 0x40c00000, v16
	v_exp_f32_e32 v27, v6
	v_add_u32_e32 v6, 0x900, v136
	ds_read2_b32 v[14:15], v6 offset1:1
	v_readlane_b32 s1, v244, 35
	v_cmp_lt_i32_e32 vcc, v195, v194
	s_lshl_b32 s16, s4, 1
	v_lshl_add_u64 v[0:1], v[0:1], 1, s[0:1]
	global_load_ushort v0, v[0:1], off
	s_waitcnt lgkmcnt(0)
	v_mul_f32_e32 v6, v27, v14
	s_waitcnt vmcnt(7)
	v_fmac_f32_e32 v12, v25, v23
	v_fmac_f32_e32 v12, v6, v5
	v_mul_f32_e32 v6, 0x40a00000, v16
	v_exp_f32_e32 v28, v6
	v_add_u32_e32 v6, 0xa00, v136
	ds_read2_b32 v[34:35], v6 offset1:1
	ds_read2st64_b32 v[6:7], v137 offset0:18 offset1:19
	s_waitcnt lgkmcnt(1)
	v_mul_f32_e32 v8, v28, v34
	s_waitcnt lgkmcnt(0)
	v_fmac_f32_e32 v12, v8, v6
	v_mul_f32_e32 v8, 4.0, v16
	v_exp_f32_e32 v29, v8
	v_add_u32_e32 v8, 0xb00, v136
	ds_read2_b32 v[36:37], v8 offset1:1
	s_waitcnt lgkmcnt(0)
	v_mul_f32_e32 v8, v29, v36
	v_fmac_f32_e32 v12, v8, v7
	v_mul_f32_e32 v8, 0x40400000, v16
	v_exp_f32_e32 v30, v8
	v_add_u32_e32 v8, 0xc00, v136
	ds_read2_b32 v[38:39], v8 offset1:1
	ds_read2st64_b32 v[8:9], v137 offset0:20 offset1:21
	s_waitcnt lgkmcnt(1)
	v_mul_f32_e32 v10, v30, v38
	s_waitcnt lgkmcnt(0)
	v_fmac_f32_e32 v12, v10, v8
	v_add_f32_e32 v10, v16, v16
	v_exp_f32_e32 v31, v10
	v_add_u32_e32 v10, 0xd00, v136
	ds_read2_b32 v[86:87], v10 offset1:1
	s_waitcnt lgkmcnt(0)
	v_mul_f32_e32 v10, v31, v86
	v_fmac_f32_e32 v12, v10, v9
	v_add_u32_e32 v10, 0xe00, v136
	ds_read2_b32 v[88:89], v10 offset1:1
	ds_read2st64_b32 v[10:11], v137 offset0:22 offset1:23
	s_waitcnt lgkmcnt(1)
	v_mul_f32_e32 v14, v32, v88
	s_waitcnt lgkmcnt(0)
	v_fmac_f32_e32 v12, v14, v10
	v_mul_f32_e32 v14, 0, v16
	v_exp_f32_e32 v33, v14
	v_add_u32_e32 v14, 0xf00, v136
	ds_read2_b32 v[90:91], v14 offset1:1
	s_waitcnt lgkmcnt(0)
	v_mul_f32_e32 v14, v33, v90
	v_fmac_f32_e32 v12, v14, v11
	global_store_dword v[2:3], v12, off nt
	v_mul_f32_e32 v12, v26, v13
	v_mul_f32_e32 v12, v4, v12
	s_waitcnt vmcnt(7)
	v_fmac_f32_e32 v12, v25, v24
	v_mul_f32_e32 v13, v27, v15
	v_fmac_f32_e32 v12, v5, v13
	v_mul_f32_e32 v13, v28, v35
	v_fmac_f32_e32 v12, v6, v13
	v_mul_f32_e32 v13, v29, v37
	v_fmac_f32_e32 v12, v7, v13
	v_mul_f32_e32 v13, v30, v39
	v_fmac_f32_e32 v12, v8, v13
	v_mul_f32_e32 v13, v31, v87
	v_fmac_f32_e32 v12, v9, v13
	v_mul_f32_e32 v13, v32, v89
	v_fmac_f32_e32 v12, v10, v13
	v_mul_f32_e32 v13, v33, v91
	v_fmac_f32_e32 v12, v11, v13
	global_store_dword v[2:3], v12, off offset:256 nt
	v_add_u32_e32 v12, 0x808, v136
	ds_read2_b32 v[12:13], v12 offset1:1
	v_add_u32_e32 v14, 0x908, v136
	ds_read2_b32 v[14:15], v14 offset1:1
	s_waitcnt lgkmcnt(1)
	v_mul_f32_e32 v12, v26, v12
	v_mul_f32_e32 v12, v4, v12
	s_waitcnt vmcnt(7)
	v_fmac_f32_e32 v12, v25, v21
	s_waitcnt lgkmcnt(0)
	v_mul_f32_e32 v14, v27, v14
	v_fmac_f32_e32 v12, v5, v14
	v_add_u32_e32 v14, 0xa08, v136
	ds_read2_b32 v[34:35], v14 offset1:1
	s_waitcnt lgkmcnt(0)
	v_mul_f32_e32 v14, v28, v34
	v_fmac_f32_e32 v12, v6, v14
	v_add_u32_e32 v14, 0xb08, v136
	ds_read2_b32 v[36:37], v14 offset1:1
	s_waitcnt lgkmcnt(0)
	v_mul_f32_e32 v14, v29, v36
	v_fmac_f32_e32 v12, v7, v14
	v_add_u32_e32 v14, 0xc08, v136
	ds_read2_b32 v[38:39], v14 offset1:1
	s_waitcnt lgkmcnt(0)
	v_mul_f32_e32 v14, v30, v38
	v_fmac_f32_e32 v12, v8, v14
	v_add_u32_e32 v14, 0xd08, v136
	ds_read2_b32 v[86:87], v14 offset1:1
	s_waitcnt lgkmcnt(0)
	v_mul_f32_e32 v14, v31, v86
	v_fmac_f32_e32 v12, v9, v14
	v_add_u32_e32 v14, 0xe08, v136
	ds_read2_b32 v[88:89], v14 offset1:1
	s_waitcnt lgkmcnt(0)
	v_mul_f32_e32 v14, v32, v88
	v_fmac_f32_e32 v12, v10, v14
	v_add_u32_e32 v14, 0xf08, v136
	ds_read2_b32 v[90:91], v14 offset1:1
	s_waitcnt lgkmcnt(0)
	v_mul_f32_e32 v14, v33, v90
	v_fmac_f32_e32 v12, v11, v14
	global_store_dword v[2:3], v12, off offset:512 nt
	v_mul_f32_e32 v12, v26, v13
	v_mul_f32_e32 v12, v4, v12
	s_waitcnt vmcnt(7)
	v_fmac_f32_e32 v12, v25, v22
	v_mul_f32_e32 v13, v27, v15
	v_fmac_f32_e32 v12, v5, v13
	v_mul_f32_e32 v13, v28, v35
	v_fmac_f32_e32 v12, v6, v13
	v_mul_f32_e32 v13, v29, v37
	v_fmac_f32_e32 v12, v7, v13
	v_mul_f32_e32 v13, v30, v39
	v_fmac_f32_e32 v12, v8, v13
	v_mul_f32_e32 v13, v31, v87
	v_fmac_f32_e32 v12, v9, v13
	v_mul_f32_e32 v13, v32, v89
	v_fmac_f32_e32 v12, v10, v13
	v_mul_f32_e32 v13, v33, v91
	v_fmac_f32_e32 v12, v11, v13
	global_store_dword v[2:3], v12, off offset:768 nt
	v_add_u32_e32 v12, 0x810, v136
	ds_read2_b32 v[12:13], v12 offset1:1
	v_add_u32_e32 v14, 0x910, v136
	ds_read2_b32 v[14:15], v14 offset1:1
	s_waitcnt lgkmcnt(1)
	v_mul_f32_e32 v12, v26, v12
	v_mul_f32_e32 v12, v4, v12
	s_waitcnt vmcnt(7)
	v_fmac_f32_e32 v12, v25, v19
	s_waitcnt lgkmcnt(0)
	v_mul_f32_e32 v14, v27, v14
	v_fmac_f32_e32 v12, v5, v14
	v_add_u32_e32 v14, 0xa10, v136
	ds_read2_b32 v[34:35], v14 offset1:1
	s_waitcnt lgkmcnt(0)
	v_mul_f32_e32 v14, v28, v34
	v_fmac_f32_e32 v12, v6, v14
	v_add_u32_e32 v14, 0xb10, v136
	ds_read2_b32 v[36:37], v14 offset1:1
	s_waitcnt lgkmcnt(0)
	v_mul_f32_e32 v14, v29, v36
	v_fmac_f32_e32 v12, v7, v14
	v_add_u32_e32 v14, 0xc10, v136
	ds_read2_b32 v[38:39], v14 offset1:1
	s_waitcnt lgkmcnt(0)
	v_mul_f32_e32 v14, v30, v38
	v_fmac_f32_e32 v12, v8, v14
	v_add_u32_e32 v14, 0xd10, v136
	ds_read2_b32 v[86:87], v14 offset1:1
	s_waitcnt lgkmcnt(0)
	v_mul_f32_e32 v14, v31, v86
	v_fmac_f32_e32 v12, v9, v14
	v_add_u32_e32 v14, 0xe10, v136
	ds_read2_b32 v[88:89], v14 offset1:1
	s_waitcnt lgkmcnt(0)
	v_mul_f32_e32 v14, v32, v88
	v_fmac_f32_e32 v12, v10, v14
	v_add_u32_e32 v14, 0xf10, v136
	ds_read2_b32 v[90:91], v14 offset1:1
	s_waitcnt lgkmcnt(0)
	v_mul_f32_e32 v14, v33, v90
	v_fmac_f32_e32 v12, v11, v14
	global_store_dword v[2:3], v12, off offset:1024 nt
	v_mul_f32_e32 v12, v26, v13
	v_mul_f32_e32 v12, v4, v12
	s_waitcnt vmcnt(7)
	v_fmac_f32_e32 v12, v25, v20
	v_mul_f32_e32 v13, v27, v15
	v_fmac_f32_e32 v12, v5, v13
	v_mul_f32_e32 v13, v28, v35
	v_fmac_f32_e32 v12, v6, v13
	v_mul_f32_e32 v13, v29, v37
	v_fmac_f32_e32 v12, v7, v13
	v_mul_f32_e32 v13, v30, v39
	v_fmac_f32_e32 v12, v8, v13
	v_mul_f32_e32 v13, v31, v87
	v_fmac_f32_e32 v12, v9, v13
	v_mul_f32_e32 v13, v32, v89
	v_fmac_f32_e32 v12, v10, v13
	v_mul_f32_e32 v13, v33, v91
	v_fmac_f32_e32 v12, v11, v13
	global_store_dword v[2:3], v12, off offset:1280 nt
	v_add_u32_e32 v12, 0x818, v136
	ds_read2_b32 v[12:13], v12 offset1:1
	v_add_u32_e32 v14, 0x918, v136
	ds_read2_b32 v[14:15], v14 offset1:1
	s_waitcnt lgkmcnt(1)
	v_mul_f32_e32 v12, v26, v12
	v_mul_f32_e32 v12, v4, v12
	s_waitcnt vmcnt(7)
	v_fmac_f32_e32 v12, v25, v18
	s_waitcnt lgkmcnt(0)
	v_mul_f32_e32 v14, v27, v14
	v_fmac_f32_e32 v12, v5, v14
	v_add_u32_e32 v14, 0xa18, v136
	ds_read2_b32 v[34:35], v14 offset1:1
	s_waitcnt lgkmcnt(0)
	v_mul_f32_e32 v14, v28, v34
	v_fmac_f32_e32 v12, v6, v14
	v_add_u32_e32 v14, 0xb18, v136
	ds_read2_b32 v[36:37], v14 offset1:1
	s_waitcnt lgkmcnt(0)
	v_mul_f32_e32 v14, v29, v36
	v_fmac_f32_e32 v12, v7, v14
	v_add_u32_e32 v14, 0xc18, v136
	ds_read2_b32 v[38:39], v14 offset1:1
	s_waitcnt lgkmcnt(0)
	v_mul_f32_e32 v14, v30, v38
	v_fmac_f32_e32 v12, v8, v14
	v_add_u32_e32 v14, 0xd18, v136
	ds_read2_b32 v[86:87], v14 offset1:1
	s_waitcnt lgkmcnt(0)
	v_mul_f32_e32 v14, v31, v86
	v_fmac_f32_e32 v12, v9, v14
	v_add_u32_e32 v14, 0xe18, v136
	ds_read2_b32 v[88:89], v14 offset1:1
	s_waitcnt lgkmcnt(0)
	v_mul_f32_e32 v14, v32, v88
	v_fmac_f32_e32 v12, v10, v14
	v_add_u32_e32 v14, 0xf18, v136
	ds_read2_b32 v[90:91], v14 offset1:1
	s_waitcnt lgkmcnt(0)
	v_mul_f32_e32 v14, v33, v90
	v_fmac_f32_e32 v12, v11, v14
	global_store_dword v[2:3], v12, off offset:1536 nt
	v_mul_f32_e32 v12, v26, v13
	v_mul_f32_e32 v4, v4, v12
	s_waitcnt vmcnt(7)
	v_fmac_f32_e32 v4, v25, v17
	v_mul_f32_e32 v12, v27, v15
	v_fmac_f32_e32 v4, v5, v12
	v_mul_f32_e32 v5, v28, v35
	v_fmac_f32_e32 v4, v6, v5
	v_mul_f32_e32 v5, v29, v37
	v_fmac_f32_e32 v4, v7, v5
	v_mul_f32_e32 v5, v30, v39
	v_fmac_f32_e32 v4, v8, v5
	v_mul_f32_e32 v5, v31, v87
	v_fmac_f32_e32 v4, v9, v5
	v_mul_f32_e32 v5, v32, v89
	v_fmac_f32_e32 v4, v10, v5
	v_mul_f32_e32 v5, v33, v91
	v_fmac_f32_e32 v4, v11, v5
	global_store_dword v[2:3], v4, off offset:1792 nt
	ds_read2_b32 v[2:3], v136 offset1:1
	s_waitcnt lgkmcnt(0)
	v_fma_f32 v4, v23, v2, 0
	v_fmac_f32_e32 v4, v24, v3
	ds_read2_b32 v[2:3], v136 offset0:2 offset1:3
	s_waitcnt lgkmcnt(0)
	v_fmac_f32_e32 v4, v21, v2
	v_fmac_f32_e32 v4, v22, v3
	ds_read2_b32 v[2:3], v136 offset0:4 offset1:5
	s_waitcnt lgkmcnt(0)
	v_fmac_f32_e32 v4, v19, v2
	v_fmac_f32_e32 v4, v20, v3
	ds_read2_b32 v[2:3], v136 offset0:6 offset1:7
	s_waitcnt lgkmcnt(0)
	v_fmac_f32_e32 v4, v18, v2
	v_fmac_f32_e32 v4, v17, v3
	ds_write_b32 v184, v4 offset:6400
	ds_read2_b32 v[2:3], v136 offset0:64 offset1:65
	s_waitcnt lgkmcnt(0)
	v_fma_f32 v4, v23, v2, 0
	v_fmac_f32_e32 v4, v24, v3
	ds_read2_b32 v[2:3], v136 offset0:66 offset1:67
	s_waitcnt lgkmcnt(0)
	v_fmac_f32_e32 v4, v21, v2
	v_fmac_f32_e32 v4, v22, v3
	ds_read2_b32 v[2:3], v136 offset0:68 offset1:69
	s_waitcnt lgkmcnt(0)
	v_fmac_f32_e32 v4, v19, v2
	v_fmac_f32_e32 v4, v20, v3
	ds_read2_b32 v[2:3], v136 offset0:70 offset1:71
	s_waitcnt lgkmcnt(0)
	v_fmac_f32_e32 v4, v18, v2
	v_fmac_f32_e32 v4, v17, v3
	ds_write_b32 v184, v4 offset:6656
	ds_read2_b32 v[2:3], v136 offset0:128 offset1:129
	s_waitcnt lgkmcnt(0)
	v_fma_f32 v4, v23, v2, 0
	v_fmac_f32_e32 v4, v24, v3
	ds_read2_b32 v[2:3], v136 offset0:130 offset1:131
	s_waitcnt lgkmcnt(0)
	v_fmac_f32_e32 v4, v21, v2
	v_fmac_f32_e32 v4, v22, v3
	ds_read2_b32 v[2:3], v136 offset0:132 offset1:133
	s_waitcnt lgkmcnt(0)
	v_fmac_f32_e32 v4, v19, v2
	v_fmac_f32_e32 v4, v20, v3
	ds_read2_b32 v[2:3], v136 offset0:134 offset1:135
	s_waitcnt lgkmcnt(0)
	v_fmac_f32_e32 v4, v18, v2
	v_fmac_f32_e32 v4, v17, v3
	ds_write_b32 v184, v4 offset:6912
	ds_read2_b32 v[2:3], v136 offset0:192 offset1:193
	s_waitcnt lgkmcnt(0)
	v_fma_f32 v4, v23, v2, 0
	v_fmac_f32_e32 v4, v24, v3
	ds_read2_b32 v[2:3], v136 offset0:194 offset1:195
	s_waitcnt lgkmcnt(0)
	v_fmac_f32_e32 v4, v21, v2
	v_fmac_f32_e32 v4, v22, v3
	ds_read2_b32 v[2:3], v136 offset0:196 offset1:197
	s_waitcnt lgkmcnt(0)
	v_fmac_f32_e32 v4, v19, v2
	v_fmac_f32_e32 v4, v20, v3
	ds_read2_b32 v[2:3], v136 offset0:198 offset1:199
	s_waitcnt lgkmcnt(0)
	v_fmac_f32_e32 v4, v18, v2
	v_fmac_f32_e32 v4, v17, v3
	ds_write_b32 v184, v4 offset:7168
	v_add_u32_e32 v2, 0x400, v136
	ds_read2_b32 v[2:3], v2 offset1:1
	s_waitcnt lgkmcnt(0)
	v_fma_f32 v4, v23, v2, 0
	v_add_u32_e32 v2, 0x408, v136
	v_fmac_f32_e32 v4, v24, v3
	ds_read2_b32 v[2:3], v2 offset1:1
	s_waitcnt lgkmcnt(0)
	v_fmac_f32_e32 v4, v21, v2
	v_add_u32_e32 v2, 0x410, v136
	v_fmac_f32_e32 v4, v22, v3
	ds_read2_b32 v[2:3], v2 offset1:1
	s_waitcnt lgkmcnt(0)
	v_fmac_f32_e32 v4, v19, v2
	v_add_u32_e32 v2, 0x418, v136
	v_fmac_f32_e32 v4, v20, v3
	ds_read2_b32 v[2:3], v2 offset1:1
	s_waitcnt lgkmcnt(0)
	v_fmac_f32_e32 v4, v18, v2
	v_fmac_f32_e32 v4, v17, v3
	ds_write_b32 v184, v4 offset:7424
	v_add_u32_e32 v2, 0x500, v136
	ds_read2_b32 v[2:3], v2 offset1:1
	s_waitcnt lgkmcnt(0)
	v_fma_f32 v4, v23, v2, 0
	v_add_u32_e32 v2, 0x508, v136
	v_fmac_f32_e32 v4, v24, v3
	ds_read2_b32 v[2:3], v2 offset1:1
	s_waitcnt lgkmcnt(0)
	v_fmac_f32_e32 v4, v21, v2
	v_add_u32_e32 v2, 0x510, v136
	v_fmac_f32_e32 v4, v22, v3
	ds_read2_b32 v[2:3], v2 offset1:1
	s_waitcnt lgkmcnt(0)
	v_fmac_f32_e32 v4, v19, v2
	v_add_u32_e32 v2, 0x518, v136
	v_fmac_f32_e32 v4, v20, v3
	ds_read2_b32 v[2:3], v2 offset1:1
	s_waitcnt lgkmcnt(0)
	v_fmac_f32_e32 v4, v18, v2
	v_fmac_f32_e32 v4, v17, v3
	ds_write_b32 v184, v4 offset:7680
	v_add_u32_e32 v2, 0x600, v136
	ds_read2_b32 v[2:3], v2 offset1:1
	s_waitcnt lgkmcnt(0)
	v_fma_f32 v4, v23, v2, 0
	v_add_u32_e32 v2, 0x608, v136
	v_fmac_f32_e32 v4, v24, v3
	ds_read2_b32 v[2:3], v2 offset1:1
	s_waitcnt lgkmcnt(0)
	v_fmac_f32_e32 v4, v21, v2
	v_add_u32_e32 v2, 0x610, v136
	v_fmac_f32_e32 v4, v22, v3
	ds_read2_b32 v[2:3], v2 offset1:1
	s_waitcnt lgkmcnt(0)
	v_fmac_f32_e32 v4, v19, v2
	v_add_u32_e32 v2, 0x618, v136
	v_fmac_f32_e32 v4, v20, v3
	ds_read2_b32 v[2:3], v2 offset1:1
	s_waitcnt lgkmcnt(0)
	v_fmac_f32_e32 v4, v18, v2
	v_fmac_f32_e32 v4, v17, v3
	ds_write_b32 v184, v4 offset:7936
	v_add_u32_e32 v2, 0x700, v136
	ds_read2_b32 v[2:3], v2 offset1:1
	s_waitcnt lgkmcnt(0)
	v_fma_f32 v4, v23, v2, 0
	v_add_u32_e32 v2, 0x708, v136
	v_fmac_f32_e32 v4, v24, v3
	ds_read2_b32 v[2:3], v2 offset1:1
	s_waitcnt lgkmcnt(0)
	v_fmac_f32_e32 v4, v21, v2
	v_add_u32_e32 v2, 0x710, v136
	v_fmac_f32_e32 v4, v22, v3
	ds_read2_b32 v[2:3], v2 offset1:1
	s_waitcnt lgkmcnt(0)
	v_fmac_f32_e32 v4, v19, v2
	v_add_u32_e32 v2, 0x718, v136
	v_fmac_f32_e32 v4, v20, v3
	ds_read2_b32 v[2:3], v2 offset1:1
	s_waitcnt lgkmcnt(0)
	v_fmac_f32_e32 v4, v18, v2
	v_fmac_f32_e32 v4, v17, v3
	ds_write_b32 v184, v4 offset:8192
	s_waitcnt lgkmcnt(0)
	s_barrier
	ds_read2st64_b32 v[2:3], v138 offset0:25 offset1:33
	s_waitcnt lgkmcnt(0)
	v_add_f32_e32 v2, 0, v2
	v_add_f32_e32 v4, v2, v3
	ds_read2st64_b32 v[2:3], v138 offset0:41 offset1:49
	s_waitcnt lgkmcnt(0)
	v_add_f32_e32 v2, v4, v2
	v_add_f32_e32 v4, v2, v3
	ds_read2st64_b32 v[2:3], v138 offset0:57 offset1:65
	s_waitcnt lgkmcnt(0)
	v_add_f32_e32 v2, v4, v2
	v_add_f32_e32 v4, v2, v3
	ds_read2st64_b32 v[2:3], v138 offset0:73 offset1:81
	s_waitcnt lgkmcnt(0)
	v_add_f32_e32 v2, v4, v2
	v_add_f32_e32 v6, v2, v3
	v_mul_f32_e32 v2, v16, v139
	v_add_u32_e32 v4, 0x1800, v136
	v_exp_f32_e32 v7, v2
	ds_read2st64_b32 v[2:3], v137 offset0:16 offset1:17
	ds_read2_b32 v[4:5], v4 offset1:1
	s_waitcnt lgkmcnt(0)
	v_pk_mul_f32 v[2:3], v[4:5], v[2:3]
	s_nop 0
	v_fma_f32 v2, v7, v6, v2
	v_add_u32_e32 v4, 0x1808, v136
	v_add_f32_e32 v6, v2, v3
	ds_read2st64_b32 v[2:3], v137 offset0:18 offset1:19
	ds_read2_b32 v[4:5], v4 offset1:1
	s_waitcnt lgkmcnt(0)
	v_pk_mul_f32 v[2:3], v[4:5], v[2:3]
	s_nop 0
	v_add_f32_e32 v2, v6, v2
	v_add_u32_e32 v4, 0x1810, v136
	v_add_f32_e32 v6, v2, v3
	ds_read2st64_b32 v[2:3], v137 offset0:20 offset1:21
	ds_read2_b32 v[4:5], v4 offset1:1
	s_waitcnt lgkmcnt(0)
	v_pk_mul_f32 v[2:3], v[4:5], v[2:3]
	s_nop 0
	v_add_f32_e32 v2, v6, v2
	v_add_u32_e32 v4, 0x1818, v136
	v_add_f32_e32 v6, v2, v3
	ds_read2st64_b32 v[2:3], v137 offset0:22 offset1:23
	ds_read2_b32 v[4:5], v4 offset1:1
	s_waitcnt lgkmcnt(0)
	v_pk_mul_f32 v[2:3], v[4:5], v[2:3]
	s_nop 0
	v_add_f32_e32 v2, v6, v2
	v_add_f32_e32 v2, v2, v3
	v_cndmask_b32_e32 v4, v193, v195, vcc
	v_mul_f32_e32 v3, v2, v2
	v_lshlrev_b32_e32 v4, 2, v4
	ds_bpermute_b32 v3, v4, v3
	v_cmp_lt_i32_e32 vcc, v196, v194
	s_waitcnt lgkmcnt(0)
	v_fmac_f32_e32 v3, v2, v2
	v_cndmask_b32_e32 v4, v193, v196, vcc
	v_lshlrev_b32_e32 v4, 2, v4
	ds_bpermute_b32 v4, v4, v3
	v_cmp_lt_i32_e32 vcc, v197, v194
	s_waitcnt vmcnt(0)
	v_lshlrev_b32_e32 v0, 16, v0
	s_waitcnt lgkmcnt(0)
	v_add_f32_e32 v3, v3, v4
	v_cndmask_b32_e32 v4, v193, v197, vcc
	v_lshlrev_b32_e32 v4, 2, v4
	ds_bpermute_b32 v4, v4, v3
	v_cmp_lt_i32_e32 vcc, v198, v194
	s_waitcnt lgkmcnt(0)
	v_add_f32_e32 v3, v3, v4
	v_cndmask_b32_e32 v4, v193, v198, vcc
	v_lshlrev_b32_e32 v4, 2, v4
	ds_bpermute_b32 v4, v4, v3
	v_cmp_lt_i32_e32 vcc, v199, v194
	s_waitcnt lgkmcnt(0)
	v_add_f32_e32 v3, v3, v4
	v_cndmask_b32_e32 v4, v193, v199, vcc
	v_lshlrev_b32_e32 v4, 2, v4
	ds_bpermute_b32 v4, v4, v3
	v_cmp_lt_i32_e32 vcc, v200, v194
	s_waitcnt lgkmcnt(0)
	v_add_f32_e32 v3, v3, v4
	v_cndmask_b32_e32 v4, v193, v200, vcc
	v_lshlrev_b32_e32 v4, 2, v4
	ds_bpermute_b32 v4, v4, v3
	s_waitcnt lgkmcnt(0)
	v_add_f32_e32 v3, v3, v4
	v_fmamk_f32 v3, v3, 0x3c800000, v183
	v_rsq_f32_e32 v3, v3
	s_nop 0
	v_mul_f32_e32 v1, v2, v3
	v_mul_f32_e32 v0, v1, v0
	v_cvt_pk_bf16_f32 v2, v0, s0
	v_readlane_b32 s0, v244, 36
	v_lshlrev_b64 v[0:1], 11, v[42:43]
	v_readlane_b32 s1, v244, 37
	v_lshlrev_b32_e32 v42, 1, v40
	s_nop 0
	v_lshl_add_u64 v[0:1], s[0:1], 0, v[0:1]
	v_lshl_add_u64 v[0:1], v[0:1], 0, s[16:17]
	v_lshl_add_u64 v[0:1], v[0:1], 0, v[42:43]
	global_store_short v[0:1], v2, off

.LBB0_549:
	s_andn2_b64 vcc, exec, s[0:1]
	s_cbranch_vccnz .LBB0_551
	v_readlane_b32 s1, v244, 58
	s_add_i32 s0, s1, 0xfffffd00
	s_bfe_u32 s1, s1, 0x30005
	v_cvt_f32_ubyte0_e32 v0, s1
	v_sub_f32_e32 v0, 0xc0a00000, v0
	s_mov_b32 s4, 0xc2fc0000
	v_cmp_gt_f32_e32 vcc, s4, v0
	s_and_b64 s[4:5], vcc, exec
	s_cselect_b32 s4, 0xffffffc0, 0
	v_cndmask_b32_e32 v1, 0, v201, vcc
	v_add_f32_e32 v0, v0, v1
	v_exp_f32_e32 v0, v0
	s_lshl_b32 s5, s0, 7
	s_and_b32 s5, s5, 0xf80
	s_lshl_b32 s16, s1, 7
	v_ldexp_f32 v0, v0, s4
	s_lshl_b32 s4, s0, 4
	s_and_b32 s4, s4, 0x7000
	v_sub_f32_e32 v0, 1.0, v0
	s_or_b32 s4, s4, s5
	v_log_f32_e32 v16, v0
	v_or_b32_e32 v0, s4, v44
	v_lshl_add_u64 v[8:9], v[68:69], 0, s[16:17]
	v_lshlrev_b32_e32 v42, 10, v0
	v_lshl_add_u64 v[0:1], v[8:9], 0, v[42:43]
	s_barrier
	global_load_dwordx4 v[0:3], v[0:1], off
	v_lshl_add_u64 v[10:11], v[70:71], 0, s[16:17]
	v_lshl_add_u64 v[4:5], v[10:11], 0, v[42:43]
	global_load_dwordx4 v[4:7], v[4:5], off
	v_mul_f32_e32 v12, v16, v142
	v_exp_f32_e32 v12, v12
	v_add_lshl_u32 v42, s4, v46, 10
	v_lshl_add_u64 v[94:95], v[8:9], 0, v[42:43]
	global_load_dwordx4 v[86:89], v[94:95], off
	v_lshl_add_u64 v[94:95], v[10:11], 0, v[42:43]
	global_load_dwordx4 v[90:93], v[94:95], off
	s_lshl_b32 s16, s0, 12
	s_lshl_b64 s[0:1], s[16:17], 2
	v_readlane_b32 s4, v244, 42
	s_add_u32 s0, s4, s0
	v_readlane_b32 s4, v244, 43
	s_addc_u32 s1, s4, s1
	s_waitcnt vmcnt(3)
	v_lshlrev_b32_e32 v14, 16, v0
	v_and_b32_e32 v15, 0xffff0000, v0
	v_pk_mul_f32 v[14:15], v[12:13], v[14:15] op_sel_hi:[0,1]
	v_cvt_pk_bf16_f32 v0, v14, v15
	v_lshlrev_b32_e32 v14, 16, v1
	v_and_b32_e32 v15, 0xffff0000, v1
	v_pk_mul_f32 v[14:15], v[12:13], v[14:15] op_sel_hi:[0,1]
	v_cvt_pk_bf16_f32 v1, v14, v15
	v_lshlrev_b32_e32 v14, 16, v2
	v_and_b32_e32 v15, 0xffff0000, v2
	v_pk_mul_f32 v[14:15], v[12:13], v[14:15] op_sel_hi:[0,1]
	v_cvt_pk_bf16_f32 v2, v14, v15
	v_lshlrev_b32_e32 v14, 16, v3
	v_and_b32_e32 v15, 0xffff0000, v3
	v_pk_mul_f32 v[12:13], v[12:13], v[14:15] op_sel_hi:[0,1]
	v_cvt_pk_bf16_f32 v3, v12, v13
	v_add_u32_e32 v12, v141, v143
	ds_write_b128 v12, v[0:3]
	s_waitcnt vmcnt(2)
	ds_write_b128 v12, v[4:7] offset:18432
	v_mul_f32_e32 v8, v16, v144
	v_exp_f32_e32 v8, v8
	s_waitcnt vmcnt(1)
	v_mov_b32_e32 v0, v86
	v_mov_b32_e32 v1, v87
	v_mov_b32_e32 v2, v88
	v_mov_b32_e32 v3, v89
	v_lshlrev_b32_e32 v10, 16, v0
	v_and_b32_e32 v11, 0xffff0000, v0
	v_pk_mul_f32 v[10:11], v[8:9], v[10:11] op_sel_hi:[0,1]
	v_cvt_pk_bf16_f32 v0, v10, v11
	v_lshlrev_b32_e32 v10, 16, v1
	v_and_b32_e32 v11, 0xffff0000, v1
	v_pk_mul_f32 v[10:11], v[8:9], v[10:11] op_sel_hi:[0,1]
	v_cvt_pk_bf16_f32 v1, v10, v11
	v_lshlrev_b32_e32 v10, 16, v2
	v_and_b32_e32 v11, 0xffff0000, v2
	v_pk_mul_f32 v[10:11], v[8:9], v[10:11] op_sel_hi:[0,1]
	v_cvt_pk_bf16_f32 v2, v10, v11
	v_lshlrev_b32_e32 v10, 16, v3
	v_and_b32_e32 v11, 0xffff0000, v3
	v_pk_mul_f32 v[8:9], v[8:9], v[10:11] op_sel_hi:[0,1]
	v_cvt_pk_bf16_f32 v3, v8, v9
	v_add_u32_e32 v8, v141, v145
	ds_write_b128 v8, v[0:3]
	s_waitcnt vmcnt(0)
	ds_write_b128 v8, v[90:93] offset:18432
	s_waitcnt lgkmcnt(0)
	s_barrier
	ds_read_b64_tr_b16 v[0:1], v185 offset:18432
	ds_read_b64_tr_b16 v[2:3], v185 offset:19008
	ds_read_b64_tr_b16 v[6:7], v186 offset:576
	ds_read_b64_tr_b16 v[4:5], v186
	ds_read_b64_tr_b16 v[8:9], v186 offset:32
	ds_read_b64_tr_b16 v[10:11], v186 offset:608
	s_waitcnt lgkmcnt(2)
	v_mfma_f32_16x16x32_bf16 v[4:7], v[0:3], v[4:7], 0
	s_waitcnt lgkmcnt(0)
	v_mfma_f32_16x16x32_bf16 v[0:3], v[0:3], v[8:11], 0
	ds_read_b64_tr_b16 v[8:9], v185 offset:23040
	ds_read_b64_tr_b16 v[10:11], v185 offset:23616
	ds_read_b64_tr_b16 v[12:13], v186 offset:4608
	ds_read_b64_tr_b16 v[14:15], v186 offset:5184
	s_waitcnt lgkmcnt(0)
	v_mfma_f32_16x16x32_bf16 v[4:7], v[8:11], v[12:15], v[4:7]
	ds_read_b64_tr_b16 v[12:13], v186 offset:4640
	ds_read_b64_tr_b16 v[14:15], v186 offset:5216
	s_waitcnt lgkmcnt(0)
	v_mfma_f32_16x16x32_bf16 v[0:3], v[8:11], v[12:15], v[0:3]
	ds_read_b64_tr_b16 v[8:9], v185 offset:27648
	ds_read_b64_tr_b16 v[10:11], v185 offset:28224
	ds_read_b64_tr_b16 v[12:13], v186 offset:9216
	ds_read_b64_tr_b16 v[14:15], v186 offset:9792
	s_waitcnt lgkmcnt(0)
	v_mfma_f32_16x16x32_bf16 v[4:7], v[8:11], v[12:15], v[4:7]
	ds_read_b64_tr_b16 v[12:13], v186 offset:9248
	ds_read_b64_tr_b16 v[14:15], v186 offset:9824
	s_waitcnt lgkmcnt(0)
	v_mfma_f32_16x16x32_bf16 v[0:3], v[8:11], v[12:15], v[0:3]
	ds_read_b64_tr_b16 v[8:9], v185 offset:32256
	ds_read_b64_tr_b16 v[10:11], v185 offset:32832
	ds_read_b64_tr_b16 v[12:13], v186 offset:13824
	ds_read_b64_tr_b16 v[14:15], v186 offset:14400
	s_waitcnt lgkmcnt(0)
	v_mfma_f32_16x16x32_bf16 v[4:7], v[8:11], v[12:15], v[4:7]
	ds_read_b64_tr_b16 v[12:13], v186 offset:13856
	ds_read_b64_tr_b16 v[14:15], v186 offset:14432
	s_waitcnt lgkmcnt(0)
	v_mfma_f32_16x16x32_bf16 v[0:3], v[8:11], v[12:15], v[0:3]
	v_lshl_add_u64 v[8:9], v[48:49], 2, s[0:1]
	s_nop 2
	global_store_dword v[8:9], v4, off
	global_store_dword v[8:9], v5, off offset:256
	global_store_dword v[8:9], v6, off offset:512
	global_store_dword v[8:9], v7, off offset:768
	global_store_dword v[8:9], v0, off offset:64
	v_lshl_add_u64 v[4:5], v[78:79], 2, s[0:1]
	global_store_dword v[4:5], v1, off offset:256
	global_store_dword v[4:5], v2, off offset:512
	global_store_dword v[4:5], v3, off offset:768
